# state scan double buffered (next 8 chunks' loads in flight while folding), forgetting-attention decay-prefix loads batched
# baseline (speedup 1.0000x reference)
; template<int THRL> __device__ __forceinline__ void attn_unit(int b,int h,int qb,const bf16*Q,const bf16*__restrict__ K,const bf16*__restrict__ V,bf16*O,const float*__restrict__ ckg,const float*__restrict__ ckoff,int ts,char*shm){
;     ...
;   { __attribute__((address_space(3))) float*ckw=(__attribute__((address_space(3))) float*)(shm3+LDS_CK); const int nck=NT*KVBLK, kofs=ts*KVBLK; float cv[16];
;     _Pragma("unroll") for(int j_=0;j_<16;++j_){const int i=tid+NW*64*j_; cv[j_]=(i<nck)?ckg[i+kofs]+ckoff[((i+kofs)>>7)*8]:0.f;}
;     _Pragma("unroll") for(int j_=0;j_<16;++j_){const int i=tid+NW*64*j_; if(i<nck)ckw[i]=cv[j_];} }
.LBB0_306:
	s_and_b32 s8, s10, -2
	s_min_i32 s8, s8, s22
	s_add_i32 s9, s30, 0x100
	s_max_i32 s8, s8, 0
	s_lshr_b32 s9, s9, 6
	s_sub_i32 s86, s9, s8
	v_mov_b32_e32 v34, v227
	s_lshl_b32 s13, s86, 6
	s_lshl_b32 s10, s8, 6
	v_readfirstlane_b32 s12, v34
	v_cmp_gt_i32_e32 vcc, s13, v34
	v_mov_b32_e32 v0, 0
	v_mov_b32_e32 v2, 0
	s_and_saveexec_b64 s[40:41], vcc
	s_cbranch_execz .LBB0_308
	v_add_u32_e32 v2, s10, v34
	v_ashrrev_i32_e32 v3, 31, v2
	v_lshl_add_u64 v[4:5], v[2:3], 2, s[16:17]
	v_ashrrev_i32_e32 v2, 4, v2
	v_and_b32_e32 v2, -8, v2
	v_ashrrev_i32_e32 v3, 31, v2
	v_lshl_add_u64 v[2:3], v[2:3], 2, s[26:27]
	global_load_dword v100, v[4:5], off
	global_load_dword v101, v[2:3], off
.LBB0_308:
	s_or_b64 exec, exec, s[40:41]
	v_add_u32_e32 v3, 0x200, v34
	v_cmp_gt_i32_e64 s[40:41], s13, v3
	s_and_saveexec_b64 s[42:43], s[40:41]
	s_cbranch_execz .LBB0_310
	v_add_u32_e32 v0, s10, v3
	s_ashr_i32 s11, s10, 31
	v_ashrrev_i32_e32 v35, 31, v34
	v_ashrrev_i32_e32 v0, 4, v0
	v_lshl_add_u64 v[4:5], v[34:35], 0, s[10:11]
	v_and_b32_e32 v6, -8, v0
	v_lshl_add_u64 v[4:5], v[4:5], 2, s[16:17]
	v_ashrrev_i32_e32 v7, 31, v6
	v_lshl_add_u64 v[6:7], v[6:7], 2, s[26:27]
	global_load_dword v102, v[4:5], off offset:2048
	global_load_dword v103, v[6:7], off
.LBB0_310:
	s_or_b64 exec, exec, s[42:43]
	v_add_u32_e32 v4, 0x400, v34
	v_cmp_gt_i32_e64 s[42:43], s13, v4
	v_mov_b32_e32 v5, 0
	v_mov_b32_e32 v6, 0
	s_and_saveexec_b64 s[44:45], s[42:43]
	s_cbranch_execz .LBB0_312
	v_add_u32_e32 v6, s10, v4
	v_ashrrev_i32_e32 v7, 31, v6
	v_lshl_add_u64 v[8:9], v[6:7], 2, s[16:17]
	v_ashrrev_i32_e32 v6, 4, v6
	v_and_b32_e32 v6, -8, v6
	v_ashrrev_i32_e32 v7, 31, v6
	v_lshl_add_u64 v[6:7], v[6:7], 2, s[26:27]
	global_load_dword v104, v[8:9], off
	global_load_dword v105, v[6:7], off
.LBB0_312:
	s_or_b64 exec, exec, s[44:45]
	v_add_u32_e32 v7, 0x600, v34
	v_cmp_gt_i32_e64 s[44:45], s13, v7
	s_and_saveexec_b64 s[46:47], s[44:45]
	s_cbranch_execz .LBB0_314
	v_add_u32_e32 v8, s10, v7
	v_ashrrev_i32_e32 v9, 31, v8
	v_ashrrev_i32_e32 v5, 4, v8
	v_lshl_add_u64 v[10:11], v[8:9], 2, s[16:17]
	v_and_b32_e32 v8, -8, v5
	v_ashrrev_i32_e32 v9, 31, v8
	v_lshl_add_u64 v[8:9], v[8:9], 2, s[26:27]
	global_load_dword v106, v[10:11], off
	global_load_dword v107, v[8:9], off
.LBB0_314:
	s_or_b64 exec, exec, s[46:47]
	v_add_u32_e32 v8, 0x800, v34
	v_cmp_gt_i32_e64 s[46:47], s13, v8
	v_mov_b32_e32 v9, 0
	v_mov_b32_e32 v10, 0
	s_and_saveexec_b64 s[48:49], s[46:47]
	s_cbranch_execz .LBB0_316
	v_add_u32_e32 v10, s10, v8
	v_ashrrev_i32_e32 v11, 31, v10
	v_lshl_add_u64 v[12:13], v[10:11], 2, s[16:17]
	v_ashrrev_i32_e32 v10, 4, v10
	v_and_b32_e32 v10, -8, v10
	v_ashrrev_i32_e32 v11, 31, v10
	v_lshl_add_u64 v[10:11], v[10:11], 2, s[26:27]
	global_load_dword v108, v[12:13], off
	global_load_dword v109, v[10:11], off
.LBB0_316:
	s_or_b64 exec, exec, s[48:49]
	v_add_u32_e32 v11, 0xa00, v34
	v_cmp_gt_i32_e64 s[48:49], s13, v11
	s_and_saveexec_b64 s[50:51], s[48:49]
	s_cbranch_execz .LBB0_318
	v_add_u32_e32 v12, s10, v11
	v_ashrrev_i32_e32 v13, 31, v12
	v_ashrrev_i32_e32 v9, 4, v12
	v_lshl_add_u64 v[14:15], v[12:13], 2, s[16:17]
	v_and_b32_e32 v12, -8, v9
	v_ashrrev_i32_e32 v13, 31, v12
	v_lshl_add_u64 v[12:13], v[12:13], 2, s[26:27]
	global_load_dword v110, v[14:15], off
	global_load_dword v111, v[12:13], off
.LBB0_318:
	s_or_b64 exec, exec, s[50:51]
	v_add_u32_e32 v12, 0xc00, v34
	v_cmp_gt_i32_e64 s[50:51], s13, v12
	v_mov_b32_e32 v13, 0
	v_mov_b32_e32 v14, 0
	s_and_saveexec_b64 s[52:53], s[50:51]
	s_cbranch_execz .LBB0_320
	v_add_u32_e32 v14, s10, v12
	v_ashrrev_i32_e32 v15, 31, v14
	v_lshl_add_u64 v[16:17], v[14:15], 2, s[16:17]
	v_ashrrev_i32_e32 v14, 4, v14
	v_and_b32_e32 v14, -8, v14
	v_ashrrev_i32_e32 v15, 31, v14
	v_lshl_add_u64 v[14:15], v[14:15], 2, s[26:27]
	global_load_dword v112, v[16:17], off
	global_load_dword v113, v[14:15], off
.LBB0_320:
	s_or_b64 exec, exec, s[52:53]
	v_add_u32_e32 v15, 0xe00, v34
	v_cmp_gt_i32_e64 s[52:53], s13, v15
	s_and_saveexec_b64 s[54:55], s[52:53]
	s_cbranch_execz .LBB0_322
	v_add_u32_e32 v16, s10, v15
	v_ashrrev_i32_e32 v17, 31, v16
	v_ashrrev_i32_e32 v13, 4, v16
	v_lshl_add_u64 v[18:19], v[16:17], 2, s[16:17]
	v_and_b32_e32 v16, -8, v13
	v_ashrrev_i32_e32 v17, 31, v16
	v_lshl_add_u64 v[16:17], v[16:17], 2, s[26:27]
	global_load_dword v114, v[18:19], off
	global_load_dword v115, v[16:17], off
; template<int THRL> __device__ __forceinline__ void attn_unit(int b,int h,int qb,const bf16*Q,const bf16*__restrict__ K,const bf16*__restrict__ V,bf16*O,const float*__restrict__ ckg,const float*__restrict__ ckoff,int ts,char*shm){
;     ...
;   { __attribute__((address_space(3))) float*ckw=(__attribute__((address_space(3))) float*)(shm3+LDS_CK); const int nck=NT*KVBLK, kofs=ts*KVBLK; float cv[16];
;     _Pragma("unroll") for(int j_=0;j_<16;++j_){const int i=tid+NW*64*j_; cv[j_]=(i<nck)?ckg[i+kofs]+ckoff[((i+kofs)>>7)*8]:0.f;}
;     _Pragma("unroll") for(int j_=0;j_<16;++j_){const int i=tid+NW*64*j_; if(i<nck)ckw[i]=cv[j_];} }
.LBB0_322:
	s_or_b64 exec, exec, s[54:55]
	v_add_u32_e32 v16, 0x1000, v34
	v_cmp_gt_i32_e64 s[54:55], s13, v16
	v_mov_b32_e32 v17, 0
	v_mov_b32_e32 v18, 0
	s_and_saveexec_b64 s[56:57], s[54:55]
	s_cbranch_execz .LBB0_324
	v_add_u32_e32 v18, s10, v16
	v_ashrrev_i32_e32 v19, 31, v18
	v_lshl_add_u64 v[20:21], v[18:19], 2, s[16:17]
	v_ashrrev_i32_e32 v18, 4, v18
	v_and_b32_e32 v18, -8, v18
	v_ashrrev_i32_e32 v19, 31, v18
	v_lshl_add_u64 v[18:19], v[18:19], 2, s[26:27]
	global_load_dword v116, v[20:21], off
	global_load_dword v117, v[18:19], off
.LBB0_324:
	s_or_b64 exec, exec, s[56:57]
	v_add_u32_e32 v19, 0x1200, v34
	v_cmp_gt_i32_e64 s[56:57], s13, v19
	s_and_saveexec_b64 s[58:59], s[56:57]
	s_cbranch_execz .LBB0_326
	v_add_u32_e32 v20, s10, v19
	v_ashrrev_i32_e32 v21, 31, v20
	v_ashrrev_i32_e32 v17, 4, v20
	v_lshl_add_u64 v[22:23], v[20:21], 2, s[16:17]
	v_and_b32_e32 v20, -8, v17
	v_ashrrev_i32_e32 v21, 31, v20
	v_lshl_add_u64 v[20:21], v[20:21], 2, s[26:27]
	global_load_dword v118, v[22:23], off
	global_load_dword v119, v[20:21], off
.LBB0_326:
	s_or_b64 exec, exec, s[58:59]
	v_add_u32_e32 v20, 0x1400, v34
	v_cmp_gt_i32_e64 s[58:59], s13, v20
	v_mov_b32_e32 v21, 0
	v_mov_b32_e32 v22, 0
	s_and_saveexec_b64 s[60:61], s[58:59]
	s_cbranch_execz .LBB0_328
	v_add_u32_e32 v22, s10, v20
	v_ashrrev_i32_e32 v23, 31, v22
	v_lshl_add_u64 v[24:25], v[22:23], 2, s[16:17]
	v_ashrrev_i32_e32 v22, 4, v22
	v_and_b32_e32 v22, -8, v22
	v_ashrrev_i32_e32 v23, 31, v22
	v_lshl_add_u64 v[22:23], v[22:23], 2, s[26:27]
	global_load_dword v120, v[24:25], off
	global_load_dword v121, v[22:23], off
.LBB0_328:
	s_or_b64 exec, exec, s[60:61]
	v_add_u32_e32 v23, 0x1600, v34
	v_cmp_gt_i32_e64 s[60:61], s13, v23
	s_and_saveexec_b64 s[62:63], s[60:61]
	s_cbranch_execz .LBB0_330
	v_add_u32_e32 v24, s10, v23
	v_ashrrev_i32_e32 v25, 31, v24
	v_ashrrev_i32_e32 v21, 4, v24
	v_lshl_add_u64 v[26:27], v[24:25], 2, s[16:17]
	v_and_b32_e32 v24, -8, v21
	v_ashrrev_i32_e32 v25, 31, v24
	v_lshl_add_u64 v[24:25], v[24:25], 2, s[26:27]
	global_load_dword v122, v[26:27], off
	global_load_dword v123, v[24:25], off
.LBB0_330:
	s_or_b64 exec, exec, s[62:63]
	v_add_u32_e32 v24, 0x1800, v34
	v_cmp_gt_i32_e64 s[62:63], s13, v24
	v_mov_b32_e32 v25, 0
	v_mov_b32_e32 v26, 0
	s_and_saveexec_b64 s[64:65], s[62:63]
	s_cbranch_execz .LBB0_332
	v_add_u32_e32 v26, s10, v24
	v_ashrrev_i32_e32 v27, 31, v26
	v_lshl_add_u64 v[28:29], v[26:27], 2, s[16:17]
	v_ashrrev_i32_e32 v26, 4, v26
	v_and_b32_e32 v26, -8, v26
	v_ashrrev_i32_e32 v27, 31, v26
	v_lshl_add_u64 v[26:27], v[26:27], 2, s[26:27]
	global_load_dword v124, v[28:29], off
	global_load_dword v125, v[26:27], off
.LBB0_332:
	s_or_b64 exec, exec, s[64:65]
	v_add_u32_e32 v27, 0x1a00, v34
	v_cmp_gt_i32_e64 s[64:65], s13, v27
	s_and_saveexec_b64 s[66:67], s[64:65]
	s_cbranch_execz .LBB0_334
	v_add_u32_e32 v28, s10, v27
	v_ashrrev_i32_e32 v29, 31, v28
	v_ashrrev_i32_e32 v25, 4, v28
	v_lshl_add_u64 v[30:31], v[28:29], 2, s[16:17]
	v_and_b32_e32 v28, -8, v25
	v_ashrrev_i32_e32 v29, 31, v28
	v_lshl_add_u64 v[28:29], v[28:29], 2, s[26:27]
	global_load_dword v126, v[30:31], off
	global_load_dword v127, v[28:29], off
.LBB0_334:
	s_or_b64 exec, exec, s[66:67]
	v_add_u32_e32 v28, 0x1c00, v34
	v_cmp_gt_i32_e64 s[66:67], s13, v28
	v_mov_b32_e32 v29, 0
	v_mov_b32_e32 v30, 0
	s_and_saveexec_b64 s[68:69], s[66:67]
	s_cbranch_execz .LBB0_336
	v_add_u32_e32 v30, s10, v28
	v_ashrrev_i32_e32 v31, 31, v30
	v_lshl_add_u64 v[32:33], v[30:31], 2, s[16:17]
	v_ashrrev_i32_e32 v30, 4, v30
	v_and_b32_e32 v30, -8, v30
	v_ashrrev_i32_e32 v31, 31, v30
	v_lshl_add_u64 v[30:31], v[30:31], 2, s[26:27]
	global_load_dword v128, v[32:33], off
	global_load_dword v129, v[30:31], off
.LBB0_336:
	s_or_b64 exec, exec, s[68:69]
	v_add_u32_e32 v31, 0x1e00, v34
	v_cmp_gt_i32_e64 s[68:69], s13, v31
	s_and_saveexec_b64 s[94:95], s[68:69]
	s_cbranch_execz .LBB0_372
	v_add_u32_e32 v32, s10, v31
	v_ashrrev_i32_e32 v33, 31, v32
	v_ashrrev_i32_e32 v29, 4, v32
	v_lshl_add_u64 v[36:37], v[32:33], 2, s[16:17]
	v_and_b32_e32 v32, -8, v29
	v_ashrrev_i32_e32 v33, 31, v32
	v_lshl_add_u64 v[32:33], v[32:33], 2, s[26:27]
	global_load_dword v130, v[36:37], off
	global_load_dword v131, v[32:33], off
	s_or_b64 exec, exec, s[94:95]
	s_waitcnt vmcnt(0)
	v_add_f32_e32 v2, v100, v101
	v_add_f32_e32 v0, v102, v103
	v_add_f32_e32 v6, v104, v105
	v_add_f32_e32 v5, v106, v107
	v_add_f32_e32 v10, v108, v109
	v_add_f32_e32 v9, v110, v111
	v_add_f32_e32 v14, v112, v113
	v_add_f32_e32 v13, v114, v115
	v_add_f32_e32 v18, v116, v117
	v_add_f32_e32 v17, v118, v119
	v_add_f32_e32 v22, v120, v121
	v_add_f32_e32 v21, v122, v123
	v_add_f32_e32 v26, v124, v125
	v_add_f32_e32 v25, v126, v127
	v_add_f32_e32 v30, v128, v129
	v_add_f32_e32 v29, v130, v131
	s_and_saveexec_b64 s[10:11], vcc
	s_cbranch_execnz .LBB0_373

; template<int THRL> __device__ __forceinline__ void attn_unit(int b,int h,int qb,const bf16*Q,const bf16*__restrict__ K,const bf16*__restrict__ V,bf16*O,const float*__restrict__ ckg,const float*__restrict__ ckoff,int ts,char*shm){
;     ...
;   { __attribute__((address_space(3))) float*ckw=(__attribute__((address_space(3))) float*)(shm3+LDS_CK); const int nck=NT*KVBLK, kofs=ts*KVBLK; float cv[16];
;     _Pragma("unroll") for(int j_=0;j_<16;++j_){const int i=tid+NW*64*j_; cv[j_]=(i<nck)?ckg[i+kofs]+ckoff[((i+kofs)>>7)*8]:0.f;}
;     _Pragma("unroll") for(int j_=0;j_<16;++j_){const int i=tid+NW*64*j_; if(i<nck)ckw[i]=cv[j_];} }
.LBB0_372:
	s_or_b64 exec, exec, s[94:95]
	s_waitcnt vmcnt(0)
	v_add_f32_e32 v2, v100, v101
	v_add_f32_e32 v0, v102, v103
	v_add_f32_e32 v6, v104, v105
	v_add_f32_e32 v5, v106, v107
	v_add_f32_e32 v10, v108, v109
	v_add_f32_e32 v9, v110, v111
	v_add_f32_e32 v14, v112, v113
	v_add_f32_e32 v13, v114, v115
	v_add_f32_e32 v18, v116, v117
	v_add_f32_e32 v17, v118, v119
	v_add_f32_e32 v22, v120, v121
	v_add_f32_e32 v21, v122, v123
	v_add_f32_e32 v26, v124, v125
	v_add_f32_e32 v25, v126, v127
	v_add_f32_e32 v30, v128, v129
	v_add_f32_e32 v29, v130, v131
	s_and_saveexec_b64 s[10:11], vcc
	s_cbranch_execz .LBB0_338

; __global__ void __launch_bounds__(NTHR, 2) fwd_mega(Args args) {
;     ...
;                 if (tid < 288) for (int pb = vcu * 576; pb < 16 * 9216; pb += G * 576) {
;                     unsigned* sp[2]; const float* dp[2]; float st[2][2]; bool ok[2];
; #pragma unroll
;                     for (int q = 0; q < 2; ++q) { const int pe = pb + tid + 288 * q; ok[q] = pe < 16 * 9216; const int pp = ok[q] ? pe : 0; const int bh = pp / 9216, vk = pp - 9216 * bh, k0 = 2 * (vk % 48);
;                         sp[q] = (unsigned*)SC + (size_t)bh * 128 * 9216 + vk; dp[q] = DEC + (size_t)bh * 128 * 96 + k0; st[q][0] = 0.f; st[q][1] = 0.f; }
;                     for (int n = 0; n < 128; n += 8) { unsigned tv[2][8]; float d0[2][8], d1[2][8];
; #pragma unroll
;                         for (int q = 0; q < 2; ++q)
; #pragma unroll
;                             for (int jj = 0; jj < 8; ++jj) { tv[q][jj] = sp[q][(size_t)(n + jj) * 9216]; d0[q][jj] = dp[q][(n + jj) * 96]; d1[q][jj] = dp[q][(n + jj) * 96 + 1]; }
.LBB0_461:
	s_waitcnt vmcnt(0)
	v_add_u32_e32 v0, s1, v247
	s_mov_b32 s2, 0x23ee0
	v_cmp_gt_i32_e64 s[40:41], s86, v0
	v_add_u32_e32 v6, 0x120, v0
	v_cmp_gt_i32_e64 s[42:43], s2, v0
	s_waitcnt lgkmcnt(0)
	v_cndmask_b32_e64 v2, 0, v0, s[40:41]
	s_mov_b32 s5, 0x38e38e39
	v_cndmask_b32_e64 v0, 0, v6, s[42:43]
	v_mul_hi_i32 v3, v2, s5
	v_mul_hi_i32 v6, v0, s5
	v_lshrrev_b32_e32 v4, 31, v3
	v_ashrrev_i32_e32 v3, 11, v3
	v_lshrrev_b32_e32 v7, 31, v6
	v_ashrrev_i32_e32 v6, 11, v6
	v_add_u32_e32 v3, v3, v4
	s_movk_i32 s6, 0xdc00
	v_add_u32_e32 v13, v6, v7
	v_mad_i32_i24 v8, v3, s6, v2
	v_mad_i32_i24 v6, v13, s6, v0
	v_mul_hi_i32 v2, v8, s33
	v_mul_hi_i32 v0, v6, s33
	v_lshrrev_b32_e32 v4, 31, v2
	v_lshrrev_b32_e32 v2, 3, v2
	v_lshrrev_b32_e32 v7, 31, v0
	v_lshrrev_b32_e32 v0, 3, v0
	v_add_u32_e32 v2, v2, v4
	v_add_u32_e32 v0, v0, v7
	v_mul_lo_u32 v2, v2, 48
	v_mul_lo_u32 v0, v0, 48
	v_sub_u32_e32 v2, v8, v2
	v_sub_u32_e32 v0, v6, v0
	v_lshlrev_b32_e32 v2, 1, v2
	v_lshlrev_b32_e32 v12, 1, v0
	v_mul_hi_i32_i24_e32 v11, 0x480000, v3
	v_mul_i32_i24_e32 v10, 0x480000, v3
	v_ashrrev_i32_e32 v9, 31, v8
	v_mul_hi_i32_i24_e32 v5, 0xc000, v3
	v_mul_i32_i24_e32 v4, 0xc000, v3
	v_ashrrev_i32_e32 v3, 31, v2
	v_mul_hi_i32_i24_e32 v15, 0x480000, v13
	v_mul_i32_i24_e32 v14, 0x480000, v13
	v_ashrrev_i32_e32 v7, 31, v6
	v_mul_hi_i32_i24_e32 v17, 0xc000, v13
	v_mul_i32_i24_e32 v16, 0xc000, v13
	v_ashrrev_i32_e32 v13, 31, v12
	v_mov_b32_e32 v30, 0
	v_lshl_add_u64 v[2:3], v[2:3], 2, v[4:5]
	v_lshl_add_u64 v[4:5], v[12:13], 2, v[16:17]
	v_lshl_add_u64 v[6:7], v[6:7], 2, v[14:15]
	v_lshl_add_u64 v[8:9], v[8:9], 2, v[10:11]
	v_mov_b32_e32 v31, v30
	v_mov_b32_e32 v10, v30
	v_mov_b32_e32 v11, v30
	s_mov_b64 s[14:15], exec
	s_add_u32 s98, s74, 0x31a00000
	s_addc_u32 s99, s75, 0
	s_mov_b64 s[100:101], s[98:99]
	s_add_u32 s6, s74, 0x200000
	s_addc_u32 s7, s75, 0
	v_mov_b32_e32 v82, v8
	v_mov_b32_e32 v90, v6
	v_add_u32_e32 v83, 0x9000, v8
	v_add_u32_e32 v91, 0x9000, v6
	v_add_u32_e32 v84, 0x12000, v8
	v_add_u32_e32 v92, 0x12000, v6
	v_add_u32_e32 v85, 0x1b000, v8
	v_add_u32_e32 v93, 0x1b000, v6
	v_add_u32_e32 v86, 0x24000, v8
	v_add_u32_e32 v94, 0x24000, v6
	v_add_u32_e32 v87, 0x2d000, v8
	v_add_u32_e32 v95, 0x2d000, v6
	v_add_u32_e32 v88, 0x36000, v8
	v_add_u32_e32 v96, 0x36000, v6
	v_add_u32_e32 v89, 0x3f000, v8
	v_add_u32_e32 v97, 0x3f000, v6
	global_load_dword v100, v82, s[98:99]
	global_load_dword v101, v83, s[98:99]
	global_load_dword v102, v84, s[98:99]
	global_load_dword v103, v85, s[98:99]
	global_load_dword v104, v86, s[98:99]
	global_load_dword v105, v87, s[98:99]
	global_load_dword v106, v88, s[98:99]
	global_load_dword v107, v89, s[98:99]
	global_load_dwordx2 v[116:117], v2, s[6:7]
	global_load_dwordx2 v[118:119], v2, s[6:7] offset:384
	global_load_dwordx2 v[120:121], v2, s[6:7] offset:768
	global_load_dwordx2 v[122:123], v2, s[6:7] offset:1152
	global_load_dwordx2 v[124:125], v2, s[6:7] offset:1536
	global_load_dwordx2 v[126:127], v2, s[6:7] offset:1920
	global_load_dwordx2 v[128:129], v2, s[6:7] offset:2304
	global_load_dwordx2 v[130:131], v2, s[6:7] offset:2688
	global_load_dword v108, v90, s[98:99]
	global_load_dword v109, v91, s[98:99]
	global_load_dword v110, v92, s[98:99]
	global_load_dword v111, v93, s[98:99]
	global_load_dword v112, v94, s[98:99]
	global_load_dword v113, v95, s[98:99]
	global_load_dword v114, v96, s[98:99]
	global_load_dword v115, v97, s[98:99]
	global_load_dwordx2 v[132:133], v4, s[6:7]
	global_load_dwordx2 v[134:135], v4, s[6:7] offset:384
	global_load_dwordx2 v[136:137], v4, s[6:7] offset:768
	global_load_dwordx2 v[138:139], v4, s[6:7] offset:1152
	global_load_dwordx2 v[140:141], v4, s[6:7] offset:1536
	global_load_dwordx2 v[142:143], v4, s[6:7] offset:1920
	global_load_dwordx2 v[144:145], v4, s[6:7] offset:2304
	global_load_dwordx2 v[146:147], v4, s[6:7] offset:2688
	s_add_u32 s98, s98, 0x48000
	s_addc_u32 s99, s99, 0
	s_add_u32 s6, s6, 0xc00
	s_addc_u32 s7, s7, 0
	global_load_dword v150, v82, s[98:99]
	global_load_dword v151, v83, s[98:99]
	global_load_dword v152, v84, s[98:99]
	global_load_dword v153, v85, s[98:99]
	global_load_dword v154, v86, s[98:99]
	global_load_dword v155, v87, s[98:99]
	global_load_dword v156, v88, s[98:99]
	global_load_dword v157, v89, s[98:99]
	global_load_dwordx2 v[166:167], v2, s[6:7]
	global_load_dwordx2 v[168:169], v2, s[6:7] offset:384
	global_load_dwordx2 v[170:171], v2, s[6:7] offset:768
	global_load_dwordx2 v[172:173], v2, s[6:7] offset:1152
	global_load_dwordx2 v[174:175], v2, s[6:7] offset:1536
	global_load_dwordx2 v[176:177], v2, s[6:7] offset:1920
	global_load_dwordx2 v[178:179], v2, s[6:7] offset:2304
	global_load_dwordx2 v[180:181], v2, s[6:7] offset:2688
	global_load_dword v158, v90, s[98:99]
	global_load_dword v159, v91, s[98:99]
	global_load_dword v160, v92, s[98:99]
	global_load_dword v161, v93, s[98:99]
	global_load_dword v162, v94, s[98:99]
	global_load_dword v163, v95, s[98:99]
	global_load_dword v164, v96, s[98:99]
	global_load_dword v165, v97, s[98:99]
	global_load_dwordx2 v[182:183], v4, s[6:7]
	global_load_dwordx2 v[184:185], v4, s[6:7] offset:384
	global_load_dwordx2 v[186:187], v4, s[6:7] offset:768
	global_load_dwordx2 v[188:189], v4, s[6:7] offset:1152
	global_load_dwordx2 v[190:191], v4, s[6:7] offset:1536
	global_load_dwordx2 v[192:193], v4, s[6:7] offset:1920
	global_load_dwordx2 v[194:195], v4, s[6:7] offset:2304
	global_load_dwordx2 v[196:197], v4, s[6:7] offset:2688
	s_add_u32 s98, s98, 0x48000
	s_addc_u32 s99, s99, 0
	s_add_u32 s6, s6, 0xc00
	s_addc_u32 s7, s7, 0
	s_waitcnt vmcnt(32)
; DI unsigned pk2(float lo, float hi) { return cvtpk(lo, hi); }
; __global__ void __launch_bounds__(NTHR, 2) fwd_mega(Args args) {
;     ...
;                     for (int n = 0; n < 128; n += 8) { unsigned tv[2][8]; float d0[2][8], d1[2][8];
; #pragma unroll
;                         for (int q = 0; q < 2; ++q)
; #pragma unroll
;                             for (int jj = 0; jj < 8; ++jj) { tv[q][jj] = sp[q][(size_t)(n + jj) * 9216]; d0[q][jj] = dp[q][(n + jj) * 96]; d1[q][jj] = dp[q][(n + jj) * 96 + 1]; }
; #pragma unroll
;                         for (int q = 0; q < 2; ++q) if (ok[q]) {
; #pragma unroll
;                             for (int jj = 0; jj < 8; ++jj) { sp[q][(size_t)(n + jj) * 9216] = pk2(st[q][0], st[q][1]);
;                                 st[q][0] = st[q][0] * d0[q][jj] + bflo(tv[q][jj]); st[q][1] = st[q][1] * d1[q][jj] + bfhi(tv[q][jj]); } } } }
	s_and_b64 exec, s[14:15], s[40:41]
	v_cvt_pk_bf16_f32 v198, v30, v31
	v_lshlrev_b32_e32 v199, 16, v100
	v_and_b32_e32 v200, 0xffff0000, v100
	global_store_dword v82, v198, s[100:101]
	v_fma_f32 v30, v30, v116, v199
	v_fma_f32 v31, v31, v117, v200
	v_cvt_pk_bf16_f32 v201, v30, v31
	v_lshlrev_b32_e32 v202, 16, v101
	v_and_b32_e32 v203, 0xffff0000, v101
	global_store_dword v83, v201, s[100:101]
	v_fma_f32 v30, v30, v118, v202
	v_fma_f32 v31, v31, v119, v203
	v_cvt_pk_bf16_f32 v204, v30, v31
	v_lshlrev_b32_e32 v205, 16, v102
	v_and_b32_e32 v206, 0xffff0000, v102
	global_store_dword v84, v204, s[100:101]
	v_fma_f32 v30, v30, v120, v205
	v_fma_f32 v31, v31, v121, v206
	v_cvt_pk_bf16_f32 v207, v30, v31
	v_lshlrev_b32_e32 v208, 16, v103
	v_and_b32_e32 v209, 0xffff0000, v103
	global_store_dword v85, v207, s[100:101]
	v_fma_f32 v30, v30, v122, v208
	v_fma_f32 v31, v31, v123, v209
	v_cvt_pk_bf16_f32 v198, v30, v31
	v_lshlrev_b32_e32 v199, 16, v104
	v_and_b32_e32 v200, 0xffff0000, v104
	global_store_dword v86, v198, s[100:101]
	v_fma_f32 v30, v30, v124, v199
	v_fma_f32 v31, v31, v125, v200
	v_cvt_pk_bf16_f32 v201, v30, v31
	v_lshlrev_b32_e32 v202, 16, v105
	v_and_b32_e32 v203, 0xffff0000, v105
	global_store_dword v87, v201, s[100:101]
	v_fma_f32 v30, v30, v126, v202
	v_fma_f32 v31, v31, v127, v203
	v_cvt_pk_bf16_f32 v204, v30, v31
	v_lshlrev_b32_e32 v205, 16, v106
	v_and_b32_e32 v206, 0xffff0000, v106
	global_store_dword v88, v204, s[100:101]
	v_fma_f32 v30, v30, v128, v205
	v_fma_f32 v31, v31, v129, v206
	v_cvt_pk_bf16_f32 v207, v30, v31
	v_lshlrev_b32_e32 v208, 16, v107
	v_and_b32_e32 v209, 0xffff0000, v107
	global_store_dword v89, v207, s[100:101]
	v_fma_f32 v30, v30, v130, v208
	v_fma_f32 v31, v31, v131, v209
	s_and_b64 exec, s[14:15], s[42:43]
	v_cvt_pk_bf16_f32 v198, v10, v11
	v_lshlrev_b32_e32 v199, 16, v108
	v_and_b32_e32 v200, 0xffff0000, v108
	global_store_dword v90, v198, s[100:101]
	v_fma_f32 v10, v10, v132, v199
	v_fma_f32 v11, v11, v133, v200
	v_cvt_pk_bf16_f32 v201, v10, v11
	v_lshlrev_b32_e32 v202, 16, v109
	v_and_b32_e32 v203, 0xffff0000, v109
	global_store_dword v91, v201, s[100:101]
	v_fma_f32 v10, v10, v134, v202
	v_fma_f32 v11, v11, v135, v203
	v_cvt_pk_bf16_f32 v204, v10, v11
	v_lshlrev_b32_e32 v205, 16, v110
	v_and_b32_e32 v206, 0xffff0000, v110
	global_store_dword v92, v204, s[100:101]
	v_fma_f32 v10, v10, v136, v205
	v_fma_f32 v11, v11, v137, v206
	v_cvt_pk_bf16_f32 v207, v10, v11
	v_lshlrev_b32_e32 v208, 16, v111
	v_and_b32_e32 v209, 0xffff0000, v111
	global_store_dword v93, v207, s[100:101]
	v_fma_f32 v10, v10, v138, v208
	v_fma_f32 v11, v11, v139, v209
	v_cvt_pk_bf16_f32 v198, v10, v11
	v_lshlrev_b32_e32 v199, 16, v112
	v_and_b32_e32 v200, 0xffff0000, v112
	global_store_dword v94, v198, s[100:101]
	v_fma_f32 v10, v10, v140, v199
	v_fma_f32 v11, v11, v141, v200
	v_cvt_pk_bf16_f32 v201, v10, v11
	v_lshlrev_b32_e32 v202, 16, v113
	v_and_b32_e32 v203, 0xffff0000, v113
	global_store_dword v95, v201, s[100:101]
	v_fma_f32 v10, v10, v142, v202
	v_fma_f32 v11, v11, v143, v203
	v_cvt_pk_bf16_f32 v204, v10, v11
	v_lshlrev_b32_e32 v205, 16, v114
	v_and_b32_e32 v206, 0xffff0000, v114
	global_store_dword v96, v204, s[100:101]
	v_fma_f32 v10, v10, v144, v205
	v_fma_f32 v11, v11, v145, v206
	v_cvt_pk_bf16_f32 v207, v10, v11
	v_lshlrev_b32_e32 v208, 16, v115
	v_and_b32_e32 v209, 0xffff0000, v115
	global_store_dword v97, v207, s[100:101]
	v_fma_f32 v10, v10, v146, v208
	v_fma_f32 v11, v11, v147, v209
	s_mov_b64 exec, s[14:15]
	s_add_u32 s100, s100, 0x48000
	s_addc_u32 s101, s101, 0
	s_mov_b32 s2, 7
.Lscan_loop:
	global_load_dword v100, v82, s[98:99]
	global_load_dword v101, v83, s[98:99]
	global_load_dword v102, v84, s[98:99]
	global_load_dword v103, v85, s[98:99]
	global_load_dword v104, v86, s[98:99]
	global_load_dword v105, v87, s[98:99]
	global_load_dword v106, v88, s[98:99]
	global_load_dword v107, v89, s[98:99]
	global_load_dwordx2 v[116:117], v2, s[6:7]
	global_load_dwordx2 v[118:119], v2, s[6:7] offset:384
	global_load_dwordx2 v[120:121], v2, s[6:7] offset:768
	global_load_dwordx2 v[122:123], v2, s[6:7] offset:1152
	global_load_dwordx2 v[124:125], v2, s[6:7] offset:1536
	global_load_dwordx2 v[126:127], v2, s[6:7] offset:1920
	global_load_dwordx2 v[128:129], v2, s[6:7] offset:2304
	global_load_dwordx2 v[130:131], v2, s[6:7] offset:2688
	global_load_dword v108, v90, s[98:99]
	global_load_dword v109, v91, s[98:99]
	global_load_dword v110, v92, s[98:99]
	global_load_dword v111, v93, s[98:99]
	global_load_dword v112, v94, s[98:99]
	global_load_dword v113, v95, s[98:99]
	global_load_dword v114, v96, s[98:99]
	global_load_dword v115, v97, s[98:99]
	global_load_dwordx2 v[132:133], v4, s[6:7]
	global_load_dwordx2 v[134:135], v4, s[6:7] offset:384
	global_load_dwordx2 v[136:137], v4, s[6:7] offset:768
	global_load_dwordx2 v[138:139], v4, s[6:7] offset:1152
	global_load_dwordx2 v[140:141], v4, s[6:7] offset:1536
	global_load_dwordx2 v[142:143], v4, s[6:7] offset:1920
	global_load_dwordx2 v[144:145], v4, s[6:7] offset:2304
	global_load_dwordx2 v[146:147], v4, s[6:7] offset:2688
	s_add_u32 s98, s98, 0x48000
	s_addc_u32 s99, s99, 0
	s_add_u32 s6, s6, 0xc00
	s_addc_u32 s7, s7, 0
	s_waitcnt vmcnt(48)
; DI unsigned pk2(float lo, float hi) { return cvtpk(lo, hi); }
; __global__ void __launch_bounds__(NTHR, 2) fwd_mega(Args args) {
;     ...
;                     for (int n = 0; n < 128; n += 8) { unsigned tv[2][8]; float d0[2][8], d1[2][8];
; #pragma unroll
;                         for (int q = 0; q < 2; ++q)
; #pragma unroll
;                             for (int jj = 0; jj < 8; ++jj) { tv[q][jj] = sp[q][(size_t)(n + jj) * 9216]; d0[q][jj] = dp[q][(n + jj) * 96]; d1[q][jj] = dp[q][(n + jj) * 96 + 1]; }
; #pragma unroll
;                         for (int q = 0; q < 2; ++q) if (ok[q]) {
; #pragma unroll
;                             for (int jj = 0; jj < 8; ++jj) { sp[q][(size_t)(n + jj) * 9216] = pk2(st[q][0], st[q][1]);
;                                 st[q][0] = st[q][0] * d0[q][jj] + bflo(tv[q][jj]); st[q][1] = st[q][1] * d1[q][jj] + bfhi(tv[q][jj]); } } } }
	s_and_b64 exec, s[14:15], s[40:41]
	v_cvt_pk_bf16_f32 v198, v30, v31
	v_lshlrev_b32_e32 v199, 16, v150
	v_and_b32_e32 v200, 0xffff0000, v150
	global_store_dword v82, v198, s[100:101]
	v_fma_f32 v30, v30, v166, v199
	v_fma_f32 v31, v31, v167, v200
	v_cvt_pk_bf16_f32 v201, v30, v31
	v_lshlrev_b32_e32 v202, 16, v151
	v_and_b32_e32 v203, 0xffff0000, v151
	global_store_dword v83, v201, s[100:101]
	v_fma_f32 v30, v30, v168, v202
	v_fma_f32 v31, v31, v169, v203
	v_cvt_pk_bf16_f32 v204, v30, v31
	v_lshlrev_b32_e32 v205, 16, v152
	v_and_b32_e32 v206, 0xffff0000, v152
	global_store_dword v84, v204, s[100:101]
	v_fma_f32 v30, v30, v170, v205
	v_fma_f32 v31, v31, v171, v206
	v_cvt_pk_bf16_f32 v207, v30, v31
	v_lshlrev_b32_e32 v208, 16, v153
	v_and_b32_e32 v209, 0xffff0000, v153
	global_store_dword v85, v207, s[100:101]
	v_fma_f32 v30, v30, v172, v208
	v_fma_f32 v31, v31, v173, v209
	v_cvt_pk_bf16_f32 v198, v30, v31
	v_lshlrev_b32_e32 v199, 16, v154
	v_and_b32_e32 v200, 0xffff0000, v154
	global_store_dword v86, v198, s[100:101]
	v_fma_f32 v30, v30, v174, v199
	v_fma_f32 v31, v31, v175, v200
	v_cvt_pk_bf16_f32 v201, v30, v31
	v_lshlrev_b32_e32 v202, 16, v155
	v_and_b32_e32 v203, 0xffff0000, v155
	global_store_dword v87, v201, s[100:101]
	v_fma_f32 v30, v30, v176, v202
	v_fma_f32 v31, v31, v177, v203
	v_cvt_pk_bf16_f32 v204, v30, v31
	v_lshlrev_b32_e32 v205, 16, v156
	v_and_b32_e32 v206, 0xffff0000, v156
	global_store_dword v88, v204, s[100:101]
	v_fma_f32 v30, v30, v178, v205
	v_fma_f32 v31, v31, v179, v206
	v_cvt_pk_bf16_f32 v207, v30, v31
	v_lshlrev_b32_e32 v208, 16, v157
	v_and_b32_e32 v209, 0xffff0000, v157
	global_store_dword v89, v207, s[100:101]
	v_fma_f32 v30, v30, v180, v208
	v_fma_f32 v31, v31, v181, v209
	s_and_b64 exec, s[14:15], s[42:43]
	v_cvt_pk_bf16_f32 v198, v10, v11
	v_lshlrev_b32_e32 v199, 16, v158
	v_and_b32_e32 v200, 0xffff0000, v158
	global_store_dword v90, v198, s[100:101]
	v_fma_f32 v10, v10, v182, v199
	v_fma_f32 v11, v11, v183, v200
	v_cvt_pk_bf16_f32 v201, v10, v11
	v_lshlrev_b32_e32 v202, 16, v159
	v_and_b32_e32 v203, 0xffff0000, v159
	global_store_dword v91, v201, s[100:101]
	v_fma_f32 v10, v10, v184, v202
	v_fma_f32 v11, v11, v185, v203
	v_cvt_pk_bf16_f32 v204, v10, v11
	v_lshlrev_b32_e32 v205, 16, v160
	v_and_b32_e32 v206, 0xffff0000, v160
	global_store_dword v92, v204, s[100:101]
	v_fma_f32 v10, v10, v186, v205
	v_fma_f32 v11, v11, v187, v206
	v_cvt_pk_bf16_f32 v207, v10, v11
	v_lshlrev_b32_e32 v208, 16, v161
	v_and_b32_e32 v209, 0xffff0000, v161
	global_store_dword v93, v207, s[100:101]
	v_fma_f32 v10, v10, v188, v208
	v_fma_f32 v11, v11, v189, v209
	v_cvt_pk_bf16_f32 v198, v10, v11
	v_lshlrev_b32_e32 v199, 16, v162
	v_and_b32_e32 v200, 0xffff0000, v162
	global_store_dword v94, v198, s[100:101]
	v_fma_f32 v10, v10, v190, v199
	v_fma_f32 v11, v11, v191, v200
	v_cvt_pk_bf16_f32 v201, v10, v11
	v_lshlrev_b32_e32 v202, 16, v163
	v_and_b32_e32 v203, 0xffff0000, v163
	global_store_dword v95, v201, s[100:101]
	v_fma_f32 v10, v10, v192, v202
	v_fma_f32 v11, v11, v193, v203
	v_cvt_pk_bf16_f32 v204, v10, v11
	v_lshlrev_b32_e32 v205, 16, v164
	v_and_b32_e32 v206, 0xffff0000, v164
	global_store_dword v96, v204, s[100:101]
	v_fma_f32 v10, v10, v194, v205
	v_fma_f32 v11, v11, v195, v206
	v_cvt_pk_bf16_f32 v207, v10, v11
	v_lshlrev_b32_e32 v208, 16, v165
	v_and_b32_e32 v209, 0xffff0000, v165
	global_store_dword v97, v207, s[100:101]
	v_fma_f32 v10, v10, v196, v208
	v_fma_f32 v11, v11, v197, v209
	s_mov_b64 exec, s[14:15]
	s_add_u32 s100, s100, 0x48000
	s_addc_u32 s101, s101, 0
	global_load_dword v150, v82, s[98:99]
	global_load_dword v151, v83, s[98:99]
	global_load_dword v152, v84, s[98:99]
	global_load_dword v153, v85, s[98:99]
	global_load_dword v154, v86, s[98:99]
	global_load_dword v155, v87, s[98:99]
	global_load_dword v156, v88, s[98:99]
	global_load_dword v157, v89, s[98:99]
	global_load_dwordx2 v[166:167], v2, s[6:7]
	global_load_dwordx2 v[168:169], v2, s[6:7] offset:384
	global_load_dwordx2 v[170:171], v2, s[6:7] offset:768
	global_load_dwordx2 v[172:173], v2, s[6:7] offset:1152
	global_load_dwordx2 v[174:175], v2, s[6:7] offset:1536
	global_load_dwordx2 v[176:177], v2, s[6:7] offset:1920
	global_load_dwordx2 v[178:179], v2, s[6:7] offset:2304
	global_load_dwordx2 v[180:181], v2, s[6:7] offset:2688
	global_load_dword v158, v90, s[98:99]
	global_load_dword v159, v91, s[98:99]
	global_load_dword v160, v92, s[98:99]
	global_load_dword v161, v93, s[98:99]
	global_load_dword v162, v94, s[98:99]
	global_load_dword v163, v95, s[98:99]
	global_load_dword v164, v96, s[98:99]
	global_load_dword v165, v97, s[98:99]
	global_load_dwordx2 v[182:183], v4, s[6:7]
	global_load_dwordx2 v[184:185], v4, s[6:7] offset:384
	global_load_dwordx2 v[186:187], v4, s[6:7] offset:768
	global_load_dwordx2 v[188:189], v4, s[6:7] offset:1152
	global_load_dwordx2 v[190:191], v4, s[6:7] offset:1536
	global_load_dwordx2 v[192:193], v4, s[6:7] offset:1920
	global_load_dwordx2 v[194:195], v4, s[6:7] offset:2304
	global_load_dwordx2 v[196:197], v4, s[6:7] offset:2688
	s_add_u32 s98, s98, 0x48000
	s_addc_u32 s99, s99, 0
	s_add_u32 s6, s6, 0xc00
	s_addc_u32 s7, s7, 0
	s_waitcnt vmcnt(48)
; DI unsigned pk2(float lo, float hi) { return cvtpk(lo, hi); }
; __global__ void __launch_bounds__(NTHR, 2) fwd_mega(Args args) {
;     ...
;                     for (int n = 0; n < 128; n += 8) { unsigned tv[2][8]; float d0[2][8], d1[2][8];
; #pragma unroll
;                         for (int q = 0; q < 2; ++q)
; #pragma unroll
;                             for (int jj = 0; jj < 8; ++jj) { tv[q][jj] = sp[q][(size_t)(n + jj) * 9216]; d0[q][jj] = dp[q][(n + jj) * 96]; d1[q][jj] = dp[q][(n + jj) * 96 + 1]; }
; #pragma unroll
;                         for (int q = 0; q < 2; ++q) if (ok[q]) {
; #pragma unroll
;                             for (int jj = 0; jj < 8; ++jj) { sp[q][(size_t)(n + jj) * 9216] = pk2(st[q][0], st[q][1]);
;                                 st[q][0] = st[q][0] * d0[q][jj] + bflo(tv[q][jj]); st[q][1] = st[q][1] * d1[q][jj] + bfhi(tv[q][jj]); } } } }
	s_and_b64 exec, s[14:15], s[40:41]
	v_cvt_pk_bf16_f32 v198, v30, v31
	v_lshlrev_b32_e32 v199, 16, v100
	v_and_b32_e32 v200, 0xffff0000, v100
	global_store_dword v82, v198, s[100:101]
	v_fma_f32 v30, v30, v116, v199
	v_fma_f32 v31, v31, v117, v200
	v_cvt_pk_bf16_f32 v201, v30, v31
	v_lshlrev_b32_e32 v202, 16, v101
	v_and_b32_e32 v203, 0xffff0000, v101
	global_store_dword v83, v201, s[100:101]
	v_fma_f32 v30, v30, v118, v202
	v_fma_f32 v31, v31, v119, v203
	v_cvt_pk_bf16_f32 v204, v30, v31
	v_lshlrev_b32_e32 v205, 16, v102
	v_and_b32_e32 v206, 0xffff0000, v102
	global_store_dword v84, v204, s[100:101]
	v_fma_f32 v30, v30, v120, v205
	v_fma_f32 v31, v31, v121, v206
	v_cvt_pk_bf16_f32 v207, v30, v31
	v_lshlrev_b32_e32 v208, 16, v103
	v_and_b32_e32 v209, 0xffff0000, v103
	global_store_dword v85, v207, s[100:101]
	v_fma_f32 v30, v30, v122, v208
	v_fma_f32 v31, v31, v123, v209
	v_cvt_pk_bf16_f32 v198, v30, v31
	v_lshlrev_b32_e32 v199, 16, v104
	v_and_b32_e32 v200, 0xffff0000, v104
	global_store_dword v86, v198, s[100:101]
	v_fma_f32 v30, v30, v124, v199
	v_fma_f32 v31, v31, v125, v200
	v_cvt_pk_bf16_f32 v201, v30, v31
	v_lshlrev_b32_e32 v202, 16, v105
	v_and_b32_e32 v203, 0xffff0000, v105
	global_store_dword v87, v201, s[100:101]
	v_fma_f32 v30, v30, v126, v202
	v_fma_f32 v31, v31, v127, v203
	v_cvt_pk_bf16_f32 v204, v30, v31
	v_lshlrev_b32_e32 v205, 16, v106
	v_and_b32_e32 v206, 0xffff0000, v106
	global_store_dword v88, v204, s[100:101]
	v_fma_f32 v30, v30, v128, v205
	v_fma_f32 v31, v31, v129, v206
	v_cvt_pk_bf16_f32 v207, v30, v31
	v_lshlrev_b32_e32 v208, 16, v107
	v_and_b32_e32 v209, 0xffff0000, v107
	global_store_dword v89, v207, s[100:101]
	v_fma_f32 v30, v30, v130, v208
	v_fma_f32 v31, v31, v131, v209
	s_and_b64 exec, s[14:15], s[42:43]
	v_cvt_pk_bf16_f32 v198, v10, v11
	v_lshlrev_b32_e32 v199, 16, v108
	v_and_b32_e32 v200, 0xffff0000, v108
	global_store_dword v90, v198, s[100:101]
	v_fma_f32 v10, v10, v132, v199
	v_fma_f32 v11, v11, v133, v200
	v_cvt_pk_bf16_f32 v201, v10, v11
	v_lshlrev_b32_e32 v202, 16, v109
	v_and_b32_e32 v203, 0xffff0000, v109
	global_store_dword v91, v201, s[100:101]
	v_fma_f32 v10, v10, v134, v202
	v_fma_f32 v11, v11, v135, v203
	v_cvt_pk_bf16_f32 v204, v10, v11
	v_lshlrev_b32_e32 v205, 16, v110
	v_and_b32_e32 v206, 0xffff0000, v110
	global_store_dword v92, v204, s[100:101]
	v_fma_f32 v10, v10, v136, v205
	v_fma_f32 v11, v11, v137, v206
	v_cvt_pk_bf16_f32 v207, v10, v11
	v_lshlrev_b32_e32 v208, 16, v111
	v_and_b32_e32 v209, 0xffff0000, v111
	global_store_dword v93, v207, s[100:101]
	v_fma_f32 v10, v10, v138, v208
	v_fma_f32 v11, v11, v139, v209
	v_cvt_pk_bf16_f32 v198, v10, v11
	v_lshlrev_b32_e32 v199, 16, v112
	v_and_b32_e32 v200, 0xffff0000, v112
	global_store_dword v94, v198, s[100:101]
	v_fma_f32 v10, v10, v140, v199
	v_fma_f32 v11, v11, v141, v200
	v_cvt_pk_bf16_f32 v201, v10, v11
	v_lshlrev_b32_e32 v202, 16, v113
	v_and_b32_e32 v203, 0xffff0000, v113
	global_store_dword v95, v201, s[100:101]
	v_fma_f32 v10, v10, v142, v202
	v_fma_f32 v11, v11, v143, v203
	v_cvt_pk_bf16_f32 v204, v10, v11
	v_lshlrev_b32_e32 v205, 16, v114
	v_and_b32_e32 v206, 0xffff0000, v114
	global_store_dword v96, v204, s[100:101]
	v_fma_f32 v10, v10, v144, v205
	v_fma_f32 v11, v11, v145, v206
	v_cvt_pk_bf16_f32 v207, v10, v11
	v_lshlrev_b32_e32 v208, 16, v115
	v_and_b32_e32 v209, 0xffff0000, v115
	global_store_dword v97, v207, s[100:101]
	v_fma_f32 v10, v10, v146, v208
	v_fma_f32 v11, v11, v147, v209
	s_mov_b64 exec, s[14:15]
	s_add_u32 s100, s100, 0x48000
	s_addc_u32 s101, s101, 0
	s_sub_u32 s2, s2, 1
	s_cmp_lg_u32 s2, 0
	s_cbranch_scc1 .Lscan_loop
; DI unsigned pk2(float lo, float hi) { return cvtpk(lo, hi); }
; __global__ void __launch_bounds__(NTHR, 2) fwd_mega(Args args) {
;     ...
;                     for (int n = 0; n < 128; n += 8) { unsigned tv[2][8]; float d0[2][8], d1[2][8];
; #pragma unroll
;                         for (int q = 0; q < 2; ++q)
; #pragma unroll
;                             for (int jj = 0; jj < 8; ++jj) { tv[q][jj] = sp[q][(size_t)(n + jj) * 9216]; d0[q][jj] = dp[q][(n + jj) * 96]; d1[q][jj] = dp[q][(n + jj) * 96 + 1]; }
; #pragma unroll
;                         for (int q = 0; q < 2; ++q) if (ok[q]) {
; #pragma unroll
;                             for (int jj = 0; jj < 8; ++jj) { sp[q][(size_t)(n + jj) * 9216] = pk2(st[q][0], st[q][1]);
;                                 st[q][0] = st[q][0] * d0[q][jj] + bflo(tv[q][jj]); st[q][1] = st[q][1] * d1[q][jj] + bfhi(tv[q][jj]); } } } }
	s_waitcnt vmcnt(16)
	s_and_b64 exec, s[14:15], s[40:41]
	v_cvt_pk_bf16_f32 v198, v30, v31
	v_lshlrev_b32_e32 v199, 16, v150
	v_and_b32_e32 v200, 0xffff0000, v150
	global_store_dword v82, v198, s[100:101]
	v_fma_f32 v30, v30, v166, v199
	v_fma_f32 v31, v31, v167, v200
	v_cvt_pk_bf16_f32 v201, v30, v31
	v_lshlrev_b32_e32 v202, 16, v151
	v_and_b32_e32 v203, 0xffff0000, v151
	global_store_dword v83, v201, s[100:101]
	v_fma_f32 v30, v30, v168, v202
	v_fma_f32 v31, v31, v169, v203
	v_cvt_pk_bf16_f32 v204, v30, v31
	v_lshlrev_b32_e32 v205, 16, v152
	v_and_b32_e32 v206, 0xffff0000, v152
	global_store_dword v84, v204, s[100:101]
	v_fma_f32 v30, v30, v170, v205
	v_fma_f32 v31, v31, v171, v206
	v_cvt_pk_bf16_f32 v207, v30, v31
	v_lshlrev_b32_e32 v208, 16, v153
	v_and_b32_e32 v209, 0xffff0000, v153
	global_store_dword v85, v207, s[100:101]
	v_fma_f32 v30, v30, v172, v208
	v_fma_f32 v31, v31, v173, v209
	v_cvt_pk_bf16_f32 v198, v30, v31
	v_lshlrev_b32_e32 v199, 16, v154
	v_and_b32_e32 v200, 0xffff0000, v154
	global_store_dword v86, v198, s[100:101]
	v_fma_f32 v30, v30, v174, v199
	v_fma_f32 v31, v31, v175, v200
	v_cvt_pk_bf16_f32 v201, v30, v31
	v_lshlrev_b32_e32 v202, 16, v155
	v_and_b32_e32 v203, 0xffff0000, v155
	global_store_dword v87, v201, s[100:101]
	v_fma_f32 v30, v30, v176, v202
	v_fma_f32 v31, v31, v177, v203
	v_cvt_pk_bf16_f32 v204, v30, v31
	v_lshlrev_b32_e32 v205, 16, v156
	v_and_b32_e32 v206, 0xffff0000, v156
	global_store_dword v88, v204, s[100:101]
	v_fma_f32 v30, v30, v178, v205
	v_fma_f32 v31, v31, v179, v206
	v_cvt_pk_bf16_f32 v207, v30, v31
	v_lshlrev_b32_e32 v208, 16, v157
	v_and_b32_e32 v209, 0xffff0000, v157
	global_store_dword v89, v207, s[100:101]
	v_fma_f32 v30, v30, v180, v208
	v_fma_f32 v31, v31, v181, v209
	s_and_b64 exec, s[14:15], s[42:43]
	v_cvt_pk_bf16_f32 v198, v10, v11
	v_lshlrev_b32_e32 v199, 16, v158
	v_and_b32_e32 v200, 0xffff0000, v158
	global_store_dword v90, v198, s[100:101]
	v_fma_f32 v10, v10, v182, v199
	v_fma_f32 v11, v11, v183, v200
	v_cvt_pk_bf16_f32 v201, v10, v11
	v_lshlrev_b32_e32 v202, 16, v159
	v_and_b32_e32 v203, 0xffff0000, v159
	global_store_dword v91, v201, s[100:101]
	v_fma_f32 v10, v10, v184, v202
	v_fma_f32 v11, v11, v185, v203
	v_cvt_pk_bf16_f32 v204, v10, v11
	v_lshlrev_b32_e32 v205, 16, v160
	v_and_b32_e32 v206, 0xffff0000, v160
	global_store_dword v92, v204, s[100:101]
	v_fma_f32 v10, v10, v186, v205
	v_fma_f32 v11, v11, v187, v206
	v_cvt_pk_bf16_f32 v207, v10, v11
	v_lshlrev_b32_e32 v208, 16, v161
	v_and_b32_e32 v209, 0xffff0000, v161
	global_store_dword v93, v207, s[100:101]
	v_fma_f32 v10, v10, v188, v208
	v_fma_f32 v11, v11, v189, v209
	v_cvt_pk_bf16_f32 v198, v10, v11
	v_lshlrev_b32_e32 v199, 16, v162
	v_and_b32_e32 v200, 0xffff0000, v162
	global_store_dword v94, v198, s[100:101]
	v_fma_f32 v10, v10, v190, v199
	v_fma_f32 v11, v11, v191, v200
	v_cvt_pk_bf16_f32 v201, v10, v11
	v_lshlrev_b32_e32 v202, 16, v163
	v_and_b32_e32 v203, 0xffff0000, v163
	global_store_dword v95, v201, s[100:101]
	v_fma_f32 v10, v10, v192, v202
	v_fma_f32 v11, v11, v193, v203
	v_cvt_pk_bf16_f32 v204, v10, v11
	v_lshlrev_b32_e32 v205, 16, v164
	v_and_b32_e32 v206, 0xffff0000, v164
	global_store_dword v96, v204, s[100:101]
	v_fma_f32 v10, v10, v194, v205
	v_fma_f32 v11, v11, v195, v206
	v_cvt_pk_bf16_f32 v207, v10, v11
	v_lshlrev_b32_e32 v208, 16, v165
	v_and_b32_e32 v209, 0xffff0000, v165
	global_store_dword v97, v207, s[100:101]
	v_fma_f32 v10, v10, v196, v208
	v_fma_f32 v11, v11, v197, v209
	s_mov_b64 exec, s[14:15]
	s_add_u32 s100, s100, 0x48000
	s_addc_u32 s101, s101, 0
	s_branch .LBB0_460
